# ffn_fix loop: conv weights/bias loaded as 8 dwordx4 up front instead of 16 dwordx2 loads each followed by a full drain
# speedup vs baseline: 1.0993x; 1.0078x over previous
;     __device__ bool next(int i, Unit& u) const {
;         const long L = (long)lo + (long)i * G + c; if (L >= hi) return false; u.L = (int)L;
;         int wgid = (int)L; { const int q = nwg / NXCD, r = nwg % NXCD, xcd = wgid % NXCD, off = wgid / NXCD; wgid = (xcd < r ? xcd * (q + 1) : r * (q + 1) + (xcd - r) * q) + off; }
;         const int nig = WGM * nN, gid = wgid / nig, fm = gid * WGM, gsz = (nM - fm) < WGM ? (nM - fm) : WGM;
;         u.pm = fm + ((wgid % nig) % gsz); u.pn = (wgid % nig) / gsz; return true;
.LBB0_35:
	s_add_i32 s55, s55, 1
	s_mul_i32 s12, s55, s54
	s_mul_hi_u32 s13, s55, s89
	s_add_i32 s13, s13, s12
	s_mul_i32 s12, s55, s89
	v_readlane_b32 s14, v255, 19
	s_add_u32 s12, s12, s14
	s_addc_u32 s13, s13, s52
	s_waitcnt lgkmcnt(0)
	v_mov_b64_e32 v[2:3], 0x200
	s_nop 0
	v_cmp_lt_i64_e64 s[42:43], s[12:13], v[2:3]
	v_mov_b64_e32 v[2:3], 0x1ff
	s_nop 0
	v_cmp_gt_i64_e64 s[40:41], s[12:13], v[2:3]
	s_and_b64 vcc, exec, s[40:41]
	s_cbranch_vccnz .LBB0_41
	s_ashr_i32 s13, s12, 31
	s_lshr_b32 s13, s13, 29
	s_add_i32 s14, s12, s13
	s_and_b32 s13, s14, -8
	s_sub_i32 s15, s12, s13
	s_cmp_gt_i32 s15, -1
	s_mov_b64 s[12:13], -1
	s_cbranch_scc0 .LBB0_38
	s_lshl_b32 s34, s15, 6
	s_mov_b64 s[12:13], 0

; __device__ void phase_mix2(const Params& P, LAS unsigned char* lds, const int G, const int bid) {
;     ...
;             for (int f = 0; f < nfold; ++f) { const int sp = dir ? nseg - 1 - f : f; const int slot = tot_slot(sg0 + sp, hd, dir);
;                 const float mseg = tots[slot * 2], aseg = tots[slot * 2 + 1];
;                 const float mnew = fmaxf(aseg + m, mseg), d0 = __expf(aseg + m - mnew), d1 = __expf(mseg - mnew);
;                 const float* tp = tot + ((size_t)slot * 512 + threadIdx.x) * 36;
; #pragma unroll
;                 for (int i = 0; i < 9; ++i) C[i] = C[i] * d0 + *(const f32x4*)(tp + 4 * i) * d1;
;                 m = mnew; }
.LBB0_77:
	s_lshl_b32 s14, s10, 1
	s_ashr_i32 s15, s14, 31
	s_lshl_b64 s[14:15], s[14:15], 2
	s_add_u32 s14, s28, s14
	s_addc_u32 s15, s96, s15
	s_waitcnt lgkmcnt(0)
	global_load_dwordx2 v[2:3], v1, s[14:15]
	s_ashr_i32 s11, s10, 31
	s_lshl_b64 s[10:11], s[10:11], 9
	v_lshl_add_u64 v[42:43], s[10:11], 0, v[162:163]
	v_mov_b64_e32 v[40:41], s[52:53]
	s_nop 0
	v_mad_u64_u32 v[40:41], s[10:11], v42, s1, v[40:41]
	v_mad_i32_i24 v41, v43, s1, v41
	global_load_dwordx4 v[42:45], v[40:41], off offset:48
	global_load_dwordx4 v[46:49], v[40:41], off offset:32
	global_load_dwordx4 v[50:53], v[40:41], off offset:16
	global_load_dwordx4 v[54:57], v[40:41], off
	s_add_i32 s18, s18, 1
	s_add_i32 s19, s19, -1
	s_cmp_eq_u32 s17, s18
	s_waitcnt vmcnt(4)
	v_add_f32_e32 v0, v160, v3
	v_max_f32_e32 v3, v2, v2
	v_max_f32_e32 v160, v0, v3
	v_sub_f32_e32 v2, v2, v160
	v_sub_f32_e32 v0, v0, v160
	v_mul_f32_e32 v2, 0x3fb8aa3b, v2
	v_mul_f32_e32 v0, 0x3fb8aa3b, v0
	v_exp_f32_e32 v2, v2
	v_exp_f32_e32 v0, v0
	s_waitcnt vmcnt(0)
	v_pk_mul_f32 v[56:57], v[56:57], v[2:3] op_sel_hi:[1,0]
	v_pk_mul_f32 v[54:55], v[54:55], v[2:3] op_sel_hi:[1,0]
	v_pk_mul_f32 v[52:53], v[52:53], v[2:3] op_sel_hi:[1,0]
	v_pk_mul_f32 v[50:51], v[50:51], v[2:3] op_sel_hi:[1,0]
	v_pk_mul_f32 v[48:49], v[48:49], v[2:3] op_sel_hi:[1,0]
	v_pk_mul_f32 v[46:47], v[46:47], v[2:3] op_sel_hi:[1,0]
	v_pk_mul_f32 v[44:45], v[44:45], v[2:3] op_sel_hi:[1,0]
	v_pk_mul_f32 v[42:43], v[42:43], v[2:3] op_sel_hi:[1,0]
	v_pk_fma_f32 v[34:35], v[34:35], v[0:1], v[56:57] op_sel_hi:[1,0,1]
	v_pk_fma_f32 v[32:33], v[32:33], v[0:1], v[54:55] op_sel_hi:[1,0,1]
	v_pk_fma_f32 v[30:31], v[30:31], v[0:1], v[52:53] op_sel_hi:[1,0,1]
	v_pk_fma_f32 v[28:29], v[28:29], v[0:1], v[50:51] op_sel_hi:[1,0,1]
	v_pk_fma_f32 v[26:27], v[26:27], v[0:1], v[48:49] op_sel_hi:[1,0,1]
	v_pk_fma_f32 v[24:25], v[24:25], v[0:1], v[46:47] op_sel_hi:[1,0,1]
	v_pk_fma_f32 v[22:23], v[22:23], v[0:1], v[44:45] op_sel_hi:[1,0,1]
	v_pk_fma_f32 v[20:21], v[20:21], v[0:1], v[42:43] op_sel_hi:[1,0,1]
	global_load_dwordx4 v[42:45], v[40:41], off offset:112
	global_load_dwordx4 v[46:49], v[40:41], off offset:96
	global_load_dwordx4 v[50:53], v[40:41], off offset:80
	global_load_dwordx4 v[54:57], v[40:41], off offset:64
	s_waitcnt vmcnt(3)
	v_pk_mul_f32 v[42:43], v[2:3], v[42:43] op_sel_hi:[0,1]
	s_nop 0
	v_pk_fma_f32 v[4:5], v[4:5], v[0:1], v[42:43] op_sel_hi:[1,0,1]
	global_load_dwordx4 v[40:43], v[40:41], off offset:128
	s_waitcnt vmcnt(1)
	v_pk_mul_f32 v[56:57], v[56:57], v[2:3] op_sel_hi:[1,0]
	v_pk_mul_f32 v[54:55], v[54:55], v[2:3] op_sel_hi:[1,0]
	v_pk_mul_f32 v[52:53], v[52:53], v[2:3] op_sel_hi:[1,0]
	v_pk_mul_f32 v[50:51], v[50:51], v[2:3] op_sel_hi:[1,0]
	v_pk_mul_f32 v[48:49], v[2:3], v[48:49] op_sel_hi:[0,1]
	v_pk_mul_f32 v[46:47], v[2:3], v[46:47] op_sel_hi:[0,1]
	v_pk_mul_f32 v[44:45], v[2:3], v[44:45] op_sel_hi:[0,1]
	v_pk_fma_f32 v[18:19], v[18:19], v[0:1], v[56:57] op_sel_hi:[1,0,1]
	v_pk_fma_f32 v[16:17], v[16:17], v[0:1], v[54:55] op_sel_hi:[1,0,1]
	v_pk_fma_f32 v[14:15], v[14:15], v[0:1], v[52:53] op_sel_hi:[1,0,1]
	v_pk_fma_f32 v[12:13], v[12:13], v[0:1], v[50:51] op_sel_hi:[1,0,1]
	v_pk_fma_f32 v[10:11], v[10:11], v[0:1], v[48:49] op_sel_hi:[1,0,1]
	v_pk_fma_f32 v[8:9], v[8:9], v[0:1], v[46:47] op_sel_hi:[1,0,1]
	v_pk_fma_f32 v[6:7], v[6:7], v[0:1], v[44:45] op_sel_hi:[1,0,1]
	s_waitcnt vmcnt(0)
	v_pk_mul_f32 v[42:43], v[2:3], v[42:43] op_sel_hi:[0,1]
	v_pk_mul_f32 v[2:3], v[2:3], v[40:41] op_sel_hi:[0,1]
	v_pk_fma_f32 v[38:39], v[38:39], v[0:1], v[42:43] op_sel_hi:[1,0,1]
	v_pk_fma_f32 v[36:37], v[36:37], v[0:1], v[2:3] op_sel_hi:[1,0,1]
	s_cbranch_scc1 .LBB0_83

; __device__ void phase_mix1(const Params& P, LAS unsigned char* lds, const int G, const int bid) {
;     ...
;         float* tp = tot + ((size_t)it * 512 + threadIdx.x) * 36;
; #pragma unroll
;         for (int i = 0; i < 9; ++i) *(f32x4*)(tp + 4 * i) = C[i];
;         if (threadIdx.x == 0) { tots[it * 2] = m; tots[it * 2 + 1] = as; }
.LBB0_409:
	s_ashr_i32 s7, s6, 31
	s_lshl_b64 s[8:9], s[6:7], 9
	s_nop 1
	v_lshl_add_u64 v[6:7], s[8:9], 0, v[162:163]
	v_mov_b64_e32 v[40:41], s[2:3]
	s_nop 0
	v_mad_u64_u32 v[40:41], s[8:9], v6, s1, v[40:41]
	v_mad_i32_i24 v41, v7, s1, v41
	global_store_dwordx4 v[40:41], v[36:39], off
	global_store_dwordx4 v[40:41], v[32:35], off offset:16
	global_store_dwordx4 v[40:41], v[28:31], off offset:32
	global_store_dwordx4 v[40:41], v[24:27], off offset:48
	global_store_dwordx4 v[40:41], v[20:23], off offset:64
	global_store_dwordx4 v[40:41], v[16:19], off offset:80
	global_store_dwordx4 v[40:41], v[12:15], off offset:96
	global_store_dwordx4 v[40:41], v[2:5], off offset:112
	global_store_dwordx4 v[40:41], v[8:11], off offset:128
	s_and_saveexec_b64 s[8:9], s[78:79]
	s_cbranch_execz .LBB0_375
	s_lshl_b32 s10, s6, 1
	s_ashr_i32 s11, s10, 31
	s_lshl_b64 s[10:11], s[10:11], 2
	s_add_u32 s10, s0, s10
	v_add_f32_e32 v91, v95, v88
	s_addc_u32 s11, s14, s11
	global_store_dwordx2 v1, v[90:91], s[10:11]
	s_branch .LBB0_375

;     __device__ bool next(int i, Unit& u) const {
;         const long L = (long)lo + (long)i * G + c; if (L >= hi) return false; u.L = (int)L;
;         int wgid = (int)L; { const int q = nwg / NXCD, r = nwg % NXCD, xcd = wgid % NXCD, off = wgid / NXCD; wgid = (xcd < r ? xcd * (q + 1) : r * (q + 1) + (xcd - r) * q) + off; }
;         const int nig = WGM * nN, gid = wgid / nig, fm = gid * WGM, gsz = (nM - fm) < WGM ? (nM - fm) : WGM;
;         u.pm = fm + ((wgid % nig) % gsz); u.pn = (wgid % nig) / gsz; return true;
.LBB0_601:
	s_add_i32 s81, s81, 1
	s_mul_i32 s6, s81, s80
	s_mul_hi_u32 s7, s81, s89
	s_add_i32 s7, s7, s6
	s_mul_i32 s6, s81, s89
	s_add_u32 s6, s6, s77
	s_addc_u32 s7, s7, s53
	v_mov_b64_e32 v[2:3], 0x800
	s_nop 0
	v_cmp_lt_i64_e64 s[42:43], s[6:7], v[2:3]
	v_mov_b64_e32 v[2:3], 0x7ff
	s_nop 0
	v_cmp_gt_i64_e64 s[40:41], s[6:7], v[2:3]
	s_and_b64 vcc, exec, s[40:41]
	s_cbranch_vccnz .LBB0_607
	s_ashr_i32 s7, s6, 31
	s_lshr_b32 s7, s7, 29
	s_add_i32 s26, s6, s7
	s_and_b32 s7, s26, -8
	s_sub_i32 s28, s6, s7
	s_cmp_gt_i32 s28, -1
	s_mov_b64 s[6:7], -1
	s_cbranch_scc0 .LBB0_604
	s_lshl_b32 s44, s28, 8
	s_mov_b64 s[6:7], 0

;     __device__ bool next(int i, Unit& u) const {
;         const long L = (long)lo + (long)i * G + c; if (L >= hi) return false; u.L = (int)L;
;         int wgid = (int)L; { const int q = nwg / NXCD, r = nwg % NXCD, xcd = wgid % NXCD, off = wgid / NXCD; wgid = (xcd < r ? xcd * (q + 1) : r * (q + 1) + (xcd - r) * q) + off; }
;         const int nig = WGM * nN, gid = wgid / nig, fm = gid * WGM, gsz = (nM - fm) < WGM ? (nM - fm) : WGM;
;         u.pm = fm + ((wgid % nig) % gsz); u.pn = (wgid % nig) / gsz; return true;
.LBB0_739:
	s_add_i32 s74, s74, 1
	v_readlane_b32 s12, v255, 18
	s_mul_i32 s10, s74, s73
	s_mul_hi_u32 s11, s74, s12
	s_add_i32 s11, s11, s10
	s_mul_i32 s10, s74, s12
	s_add_u32 s10, s2, s10
	s_addc_u32 s11, s3, s11
	v_mov_b64_e32 v[2:3], 0x200
	s_nop 0
	v_cmp_lt_i64_e64 s[42:43], s[10:11], v[2:3]
	v_mov_b64_e32 v[2:3], 0x1ff
	s_nop 0
	v_cmp_gt_i64_e64 s[40:41], s[10:11], v[2:3]
	s_and_b64 vcc, exec, s[40:41]
	s_cbranch_vccnz .LBB0_745
	s_ashr_i32 s11, s10, 31
	s_lshr_b32 s11, s11, 29
	s_add_i32 s11, s10, s11
	s_and_b32 s12, s11, -8
	s_sub_i32 s18, s10, s12
	s_cmp_gt_i32 s18, -1
	s_mov_b64 s[12:13], -1
	s_cbranch_scc0 .LBB0_742
	s_lshl_b32 s19, s18, 6
	s_mov_b64 s[12:13], 0

;     __device__ bool next(int i, Unit& u) const {
;         const long L = (long)lo + (long)i * G + c; if (L >= hi) return false; u.L = (int)L;
;         int wgid = (int)L; { const int q = nwg / NXCD, r = nwg % NXCD, xcd = wgid % NXCD, off = wgid / NXCD; wgid = (xcd < r ? xcd * (q + 1) : r * (q + 1) + (xcd - r) * q) + off; }
;         const int nig = WGM * nN, gid = wgid / nig, fm = gid * WGM, gsz = (nM - fm) < WGM ? (nM - fm) : WGM;
;         u.pm = fm + ((wgid % nig) % gsz); u.pn = (wgid % nig) / gsz; return true;
.LBB0_767:
	s_add_i32 s83, s83, 1
	v_readlane_b32 s28, v255, 18
	s_mul_i32 s6, s83, s82
	s_mul_hi_u32 s7, s83, s28
	s_add_i32 s7, s7, s6
	s_mul_i32 s6, s83, s28
	s_add_u32 s6, s6, s77
	s_addc_u32 s7, s7, s54
	s_waitcnt lgkmcnt(0)
	v_mov_b64_e32 v[2:3], 0x200
	s_nop 0
	v_cmp_lt_i64_e64 s[42:43], s[6:7], v[2:3]
	v_mov_b64_e32 v[2:3], 0x1ff
	s_nop 0
	v_cmp_gt_i64_e64 s[40:41], s[6:7], v[2:3]
	s_and_b64 vcc, exec, s[40:41]
	s_cbranch_vccnz .LBB0_773
	s_ashr_i32 s7, s6, 31
	s_lshr_b32 s7, s7, 29
	s_add_i32 s7, s6, s7
	s_and_b32 s10, s7, -8
	s_sub_i32 s28, s6, s10
	s_cmp_gt_i32 s28, -1
	s_mov_b64 s[10:11], -1
	s_cbranch_scc0 .LBB0_770
	s_lshl_b32 s44, s28, 6
	s_mov_b64 s[10:11], 0

;     __device__ bool next(int i, Unit& u) const {
;         const long L = (long)lo + (long)i * G + c; if (L >= hi) return false; u.L = (int)L;
;         int wgid = (int)L; { const int q = nwg / NXCD, r = nwg % NXCD, xcd = wgid % NXCD, off = wgid / NXCD; wgid = (xcd < r ? xcd * (q + 1) : r * (q + 1) + (xcd - r) * q) + off; }
;         const int nig = WGM * nN, gid = wgid / nig, fm = gid * WGM, gsz = (nM - fm) < WGM ? (nM - fm) : WGM;
;         u.pm = fm + ((wgid % nig) % gsz); u.pn = (wgid % nig) / gsz; return true;
; __global__ void __launch_bounds__(512, 2) mega(Params P0) {
;     ...
;                 { pg8::Unit uu; int lastpm = -1; for (int i = 0; S.next(i, uu); ++i) if (uu.pm != lastpm) { ffn_fix((bf16_t*)(dob + DO_G), (const bf16_t*)(dob + DO_GR), (const bf16_t*)(dob + DO_UP), P.in[16], P.in[17], uu.pm, half); lastpm = uu.pm; } }
.LBB0_807:
	v_readlane_b32 s10, v255, 18
	s_mul_i32 s8, s15, s0
	s_mul_hi_u32 s9, s15, s10
	s_add_i32 s9, s9, s8
	s_mul_i32 s8, s15, s10
	s_add_u32 s8, s8, s77
	s_addc_u32 s9, s9, s24
	s_waitcnt lgkmcnt(0)
	v_mov_b64_e32 v[2:3], 0xff
	s_nop 0
	v_cmp_gt_i64_e32 vcc, s[8:9], v[2:3]
	s_cbranch_vccnz .LBB0_813
	s_ashr_i32 s10, s8, 31
	s_lshr_b32 s10, s10, 29
	s_add_i32 s13, s8, s10
	s_and_b32 s10, s13, -8
	s_sub_i32 s17, s8, s10
	s_cmp_gt_i32 s17, -1
	s_mov_b64 s[10:11], -1
	s_cbranch_scc0 .LBB0_810
	s_lshl_b32 s18, s17, 5
	s_mov_b64 s[10:11], 0

; __device__ __forceinline__ unsigned cvt_pk_bf16(float lo, float hi) { unsigned r; asm volatile("v_cvt_pk_bf16_f32 %0, %1, %2" : "=v"(r) : "v"(lo), "v"(hi)); return r; }
; __device__ __forceinline__ float bf_lo(unsigned w) { return __uint_as_float(w << 16); }
; __device__ __forceinline__ float bf_hi(unsigned w) { return __uint_as_float(w & 0xffff0000u); }
; __device__ void ffn_fix(bf16_t* ACT, const bf16_t* GR, const bf16_t* UP, const float* cw, const float* cb, int pm, int half) {
;     ...
;     for (int it = tid; it < 8 * 352; it += 512) { const int br = it / 352, col = (it % 352) * 8; const int group = pm * 4 + (br >> 1), which = br & 1;
;         const bool seq_first = (group % seqgroups) == 0, seq_last = (group % seqgroups) == seqgroups - 1;
;         const bf16_t* pp = which ? GR + (size_t)(group * 4 + 2) * DFF : GR + (size_t)((seq_first ? group : group - 1) * 4 + 3) * DFF;
;         const bf16_t* pc = GR + (size_t)(group * 4 + (which ? 3 : 0)) * DFF;
;         const bf16_t* pn = which ? GR + (size_t)((seq_last ? group : group + 1) * 4 + 0) * DFF : GR + (size_t)(group * 4 + 1) * DFF;
;         const float mp = (!which && seq_first) ? 0.f : 1.f, mn = (which && seq_last) ? 0.f : 1.f;
;         const u32x4 gp = *(const u32x4*)(pp + col), gc = *(const u32x4*)(pc + col), gn = *(const u32x4*)(pn + col), up = *(const u32x4*)(UP + (size_t)(group * 2 + which) * DFF + col);
;         u32x4 ov;
; #pragma unroll
;         for (int q = 0; q < 4; ++q) { const int c = col + 2 * q;
;             const float u0 = bf_lo(gp[q]) * mp * cw[c] + bf_lo(gc[q]) * cw[DFF + c] + bf_lo(gn[q]) * mn * cw[2 * DFF + c] + cb[c];
;             const float u1 = bf_hi(gp[q]) * mp * cw[c + 1] + bf_hi(gc[q]) * cw[DFF + c + 1] + bf_hi(gn[q]) * mn * cw[2 * DFF + c + 1] + cb[c + 1];
;             const f32x2 ge = gelu_pk((f32x2){u0, u1}); ov[q] = cvt_pk_bf16(ge.x * bf_lo(up[q]), ge.y * bf_hi(up[q])); }
.LBB0_813:
	v_mov_b64_e32 v[2:3], 0x100
	s_nop 0
	v_cmp_lt_i64_e32 vcc, s[8:9], v[2:3]
	s_mov_b64 s[8:9], -1
	s_cbranch_vccz .LBB0_806
	s_cmp_eq_u32 s26, s12
	s_cbranch_scc1 .LBB0_805
	v_mov_b32_e32 v33, v162
	s_movk_i32 s8, 0xb00
	s_nop 0
	v_cmp_gt_i32_e32 vcc, s8, v33
	s_and_saveexec_b64 s[8:9], vcc
	s_cbranch_execz .LBB0_804
	s_lshl_b32 s17, s26, 2
	v_lshlrev_b32_e32 v32, 3, v33
	s_mov_b64 s[10:11], 0
	s_branch .LBB0_818
.LBB0_817:
	s_or_b64 exec, exec, s[12:13]
	v_mul_i32_i24_e32 v3, 0x160, v3
	v_lshlrev_b32_e32 v3, 3, v3
	v_sub_u32_e32 v22, v32, v3
	v_mov_b64_e32 v[10:11], s[4:5]
	s_movk_i32 s18, 0x1600
	v_ashrrev_i32_e32 v23, 31, v22
	v_mad_i64_i32 v[12:13], s[12:13], v5, s18, v[10:11]
	v_lshlrev_b64 v[18:19], 1, v[22:23]
	v_or_b32_e32 v4, v6, v4
	v_mad_i64_i32 v[6:7], s[12:13], v8, s18, v[10:11]
	v_lshl_add_u64 v[8:9], v[12:13], 0, v[18:19]
	v_mad_i64_i32 v[4:5], s[12:13], v4, s18, v[10:11]
	global_load_dwordx4 v[10:13], v[8:9], off
	v_readlane_b32 s60, v255, 2
	v_readlane_b32 s61, v255, 3
	v_lshl_add_u64 v[4:5], v[4:5], 0, v[18:19]
	v_lshlrev_b64 v[22:23], 2, v[22:23]
	v_readlane_b32 s62, v255, 4
	v_readlane_b32 s63, v255, 5
	s_mov_b64 s[40:41], s[60:61]
	global_load_dwordx4 v[14:17], v[4:5], off
	v_lshl_add_u64 v[24:25], s[40:41], 0, v[22:23]
	v_lshl_add_u64 v[4:5], v[6:7], 0, v[18:19]
	global_load_dwordx2 v[30:31], v[24:25], off
	global_load_dwordx4 v[6:9], v[4:5], off
	s_mov_b64 s[42:43], s[62:63]
	v_lshl_add_u64 v[22:23], s[42:43], 0, v[22:23]
	v_lshl_or_b32 v4, v34, 1, v2
	v_mov_b64_e32 v[2:3], s[6:7]
	s_nop 0
	v_mad_i64_i32 v[2:3], s[12:13], v4, s18, v[2:3]
	v_lshl_add_u64 v[2:3], v[2:3], 0, v[18:19]
	global_load_dwordx4 v[2:5], v[2:3], off
	v_add_co_u32_e32 v76, vcc, 0x2c00, v24
	s_nop 1
	v_addc_co_u32_e32 v77, vcc, 0, v25, vcc
	v_add_co_u32_e32 v78, vcc, 0x5800, v24
	s_nop 1
	v_addc_co_u32_e32 v79, vcc, 0, v25, vcc
	global_load_dwordx4 v[44:47], v[24:25], off
	global_load_dwordx4 v[48:51], v[24:25], off offset:16
	global_load_dwordx4 v[52:55], v[76:77], off
	global_load_dwordx4 v[56:59], v[76:77], off offset:16
	global_load_dwordx4 v[60:63], v[78:79], off
	global_load_dwordx4 v[64:67], v[78:79], off offset:16
	global_load_dwordx4 v[68:71], v[22:23], off
	global_load_dwordx4 v[72:75], v[22:23], off offset:16
	s_mov_b32 s12, 0xbf3a00e3
	s_mov_b32 s34, 0x3f35f0e3
	s_mov_b32 s36, 0xbe11a98e
	s_mov_b32 s38, 0x3e027906
	s_mov_b32 s40, 0xbf38aa3b
	v_add_u32_e32 v32, 0x1000, v32
	v_readlane_b32 s64, v255, 6
	v_readlane_b32 s65, v255, 7
	v_readlane_b32 s66, v255, 8
	v_readlane_b32 s67, v255, 9
	v_readlane_b32 s68, v255, 10
	v_readlane_b32 s69, v255, 11
	v_readlane_b32 s70, v255, 12
	v_readlane_b32 s71, v255, 13
	v_readlane_b32 s72, v255, 14
	v_readlane_b32 s73, v255, 15
	v_readlane_b32 s74, v255, 16
	v_readlane_b32 s75, v255, 17
	s_waitcnt vmcnt(0)
	v_lshlrev_b32_e32 v26, 16, v10
	v_and_b32_e32 v27, 0xffff0000, v10
	v_pk_mul_f32 v[28:29], v[20:21], v[26:27] op_sel_hi:[0,1]
	v_add_co_u32_e32 v26, vcc, s83, v24
	v_lshlrev_b32_e32 v36, 16, v14
	s_nop 0
	v_addc_co_u32_e32 v27, vcc, 0, v25, vcc
	v_mov_b64_e32 v[38:39], v[52:53]
	v_and_b32_e32 v37, 0xffff0000, v14
	v_lshlrev_b32_e32 v14, 16, v2
	v_and_b32_e32 v2, 0xffff0000, v2
	s_waitcnt vmcnt(0)
	v_pk_mul_f32 v[36:37], v[38:39], v[36:37]
	s_nop 0
	v_pk_fma_f32 v[30:31], v[28:29], v[30:31], v[36:37]
	v_lshlrev_b32_e32 v28, 16, v6
	v_and_b32_e32 v29, 0xffff0000, v6
	v_pk_mul_f32 v[36:37], v[0:1], v[28:29] op_sel_hi:[0,1]
	v_add_co_u32_e32 v28, vcc, s28, v24
	s_nop 1
	v_addc_co_u32_e32 v29, vcc, 0, v25, vcc
	v_mov_b64_e32 v[38:39], v[60:61]
	s_waitcnt vmcnt(0)
	v_pk_fma_f32 v[30:31], v[36:37], v[38:39], v[30:31]
	v_mov_b64_e32 v[36:37], v[68:69]
	s_waitcnt vmcnt(0)
	v_pk_add_f32 v[36:37], v[36:37], v[30:31]
	s_nop 0
	v_and_b32_e32 v31, 0x7fffffff, v37
	v_and_b32_e32 v30, 0x7fffffff, v36
	v_pk_fma_f32 v[30:31], v[30:31], s[54:55], 1.0 op_sel_hi:[1,0,0]
	v_cmp_gt_f32_e32 vcc, 0, v36
	v_rcp_f32_e32 v38, v30
	v_rcp_f32_e32 v39, v31
	v_mov_b64_e32 v[30:31], s[12:13]
	s_mov_b32 s12, 0x3f07dc22
	v_pk_fma_f32 v[40:41], v[38:39], s[12:13], v[30:31] op_sel_hi:[1,0,0]
	s_nop 0
	v_pk_fma_f32 v[40:41], v[38:39], v[40:41], s[34:35] op_sel_hi:[1,1,0]
	s_nop 0
	v_pk_fma_f32 v[40:41], v[38:39], v[40:41], s[36:37] op_sel_hi:[1,1,0]
	s_nop 0
	v_pk_fma_f32 v[40:41], v[38:39], v[40:41], s[38:39] op_sel_hi:[1,1,0]
	s_nop 0
	v_pk_mul_f32 v[38:39], v[38:39], v[40:41]
	v_pk_mul_f32 v[40:41], v[36:37], v[36:37]
	s_nop 0
	v_pk_mul_f32 v[40:41], v[40:41], s[40:41] op_sel_hi:[1,0]
	s_nop 0
	v_exp_f32_e32 v40, v40
	v_exp_f32_e32 v41, v41
	s_nop 0
	v_pk_mul_f32 v[38:39], v[40:41], v[38:39]
	s_nop 0
	v_pk_mul_f32 v[40:41], v[36:37], v[38:39]
	v_pk_fma_f32 v[38:39], v[36:37], v[38:39], v[36:37] neg_lo:[1,0,0] neg_hi:[1,0,0]
	s_nop 0
	v_cndmask_b32_e32 v6, v38, v40, vcc
	v_cmp_gt_f32_e32 vcc, 0, v37
	v_mul_f32_e32 v6, v6, v14
	v_lshlrev_b32_e32 v14, 16, v15
	v_cndmask_b32_e32 v10, v39, v41, vcc
	v_mul_f32_e32 v2, v10, v2
	v_cvt_pk_bf16_f32 v2, v6, v2
	v_mov_b64_e32 v[36:37], v[46:47]
	v_mov_b64_e32 v[38:39], v[54:55]
	v_lshlrev_b32_e32 v10, 16, v11
	v_and_b32_e32 v11, 0xffff0000, v11
	v_and_b32_e32 v15, 0xffff0000, v15
	v_pk_mul_f32 v[10:11], v[20:21], v[10:11] op_sel_hi:[0,1]
	v_lshlrev_b32_e32 v6, 16, v7
	v_and_b32_e32 v7, 0xffff0000, v7
	v_pk_mul_f32 v[6:7], v[0:1], v[6:7] op_sel_hi:[0,1]
	s_waitcnt vmcnt(0)
	v_pk_mul_f32 v[14:15], v[38:39], v[14:15]
	s_nop 0
	v_pk_fma_f32 v[10:11], v[10:11], v[36:37], v[14:15]
	v_mov_b64_e32 v[14:15], v[62:63]
	s_waitcnt vmcnt(0)
; __device__ __forceinline__ unsigned cvt_pk_bf16(float lo, float hi) { unsigned r; asm volatile("v_cvt_pk_bf16_f32 %0, %1, %2" : "=v"(r) : "v"(lo), "v"(hi)); return r; }
; __device__ __forceinline__ float bf_lo(unsigned w) { return __uint_as_float(w << 16); }
; __device__ __forceinline__ float bf_hi(unsigned w) { return __uint_as_float(w & 0xffff0000u); }
; __device__ void ffn_fix(bf16_t* ACT, const bf16_t* GR, const bf16_t* UP, const float* cw, const float* cb, int pm, int half) {
;     ...
;         for (int q = 0; q < 4; ++q) { const int c = col + 2 * q;
;             const float u0 = bf_lo(gp[q]) * mp * cw[c] + bf_lo(gc[q]) * cw[DFF + c] + bf_lo(gn[q]) * mn * cw[2 * DFF + c] + cb[c];
;             const float u1 = bf_hi(gp[q]) * mp * cw[c + 1] + bf_hi(gc[q]) * cw[DFF + c + 1] + bf_hi(gn[q]) * mn * cw[2 * DFF + c + 1] + cb[c + 1];
;             const f32x2 ge = gelu_pk((f32x2){u0, u1}); ov[q] = cvt_pk_bf16(ge.x * bf_lo(up[q]), ge.y * bf_hi(up[q])); }
;         *(u32x4*)(ACT + (size_t)(group * 64 + (which ? 63 : 0)) * DFF + col) = ov; }
	v_pk_fma_f32 v[6:7], v[6:7], v[14:15], v[10:11]
	v_mov_b64_e32 v[10:11], v[70:71]
	s_waitcnt vmcnt(0)
	v_pk_add_f32 v[6:7], v[10:11], v[6:7]
	s_nop 0
	v_and_b32_e32 v11, 0x7fffffff, v7
	v_and_b32_e32 v10, 0x7fffffff, v6
	v_pk_fma_f32 v[10:11], v[10:11], s[54:55], 1.0 op_sel_hi:[1,0,0]
	v_cmp_gt_f32_e32 vcc, 0, v6
	v_rcp_f32_e32 v10, v10
	v_rcp_f32_e32 v11, v11
	s_nop 0
	v_pk_fma_f32 v[14:15], v[10:11], s[12:13], v[30:31] op_sel_hi:[1,0,0]
	s_nop 0
	v_pk_fma_f32 v[14:15], v[10:11], v[14:15], s[34:35] op_sel_hi:[1,1,0]
	s_nop 0
	v_pk_fma_f32 v[14:15], v[10:11], v[14:15], s[36:37] op_sel_hi:[1,1,0]
	s_nop 0
	v_pk_fma_f32 v[14:15], v[10:11], v[14:15], s[38:39] op_sel_hi:[1,1,0]
	s_nop 0
	v_pk_mul_f32 v[10:11], v[10:11], v[14:15]
	v_pk_mul_f32 v[14:15], v[6:7], v[6:7]
	s_nop 0
	v_pk_mul_f32 v[14:15], v[14:15], s[40:41] op_sel_hi:[1,0]
	s_nop 0
	v_exp_f32_e32 v14, v14
	v_exp_f32_e32 v15, v15
	s_nop 0
	v_pk_mul_f32 v[10:11], v[14:15], v[10:11]
	s_nop 0
	v_pk_mul_f32 v[14:15], v[6:7], v[10:11]
	v_pk_fma_f32 v[10:11], v[6:7], v[10:11], v[6:7] neg_lo:[1,0,0] neg_hi:[1,0,0]
	s_nop 0
	v_cndmask_b32_e32 v6, v10, v14, vcc
	v_cmp_gt_f32_e32 vcc, 0, v7
	v_lshlrev_b32_e32 v10, 16, v3
	v_and_b32_e32 v3, 0xffff0000, v3
	v_cndmask_b32_e32 v7, v11, v15, vcc
	v_mul_f32_e32 v3, v7, v3
	v_mul_f32_e32 v6, v6, v10
	v_cvt_pk_bf16_f32 v3, v6, v3
	v_mov_b64_e32 v[10:11], v[48:49]
	v_mov_b64_e32 v[36:37], v[56:57]
	v_lshlrev_b32_e32 v6, 16, v12
	v_and_b32_e32 v7, 0xffff0000, v12
	v_lshlrev_b32_e32 v14, 16, v16
	v_and_b32_e32 v15, 0xffff0000, v16
	v_pk_mul_f32 v[6:7], v[20:21], v[6:7] op_sel_hi:[0,1]
	v_lshlrev_b32_e32 v12, 16, v17
	s_waitcnt vmcnt(0)
	v_pk_mul_f32 v[14:15], v[36:37], v[14:15]
	s_nop 0
	v_pk_fma_f32 v[6:7], v[6:7], v[10:11], v[14:15]
	v_mov_b64_e32 v[14:15], v[64:65]
	v_lshlrev_b32_e32 v10, 16, v8
	v_and_b32_e32 v11, 0xffff0000, v8
	v_pk_mul_f32 v[10:11], v[0:1], v[10:11] op_sel_hi:[0,1]
	v_lshlrev_b32_e32 v8, 16, v4
	v_and_b32_e32 v4, 0xffff0000, v4
	s_waitcnt vmcnt(0)
	v_pk_fma_f32 v[6:7], v[10:11], v[14:15], v[6:7]
	v_mov_b64_e32 v[10:11], v[72:73]
	s_waitcnt vmcnt(0)
	v_pk_add_f32 v[6:7], v[10:11], v[6:7]
	s_nop 0
	v_and_b32_e32 v11, 0x7fffffff, v7
	v_and_b32_e32 v10, 0x7fffffff, v6
	v_pk_fma_f32 v[10:11], v[10:11], s[54:55], 1.0 op_sel_hi:[1,0,0]
	v_cmp_gt_f32_e32 vcc, 0, v6
	v_rcp_f32_e32 v10, v10
	v_rcp_f32_e32 v11, v11
	s_nop 0
	v_pk_fma_f32 v[14:15], v[10:11], s[12:13], v[30:31] op_sel_hi:[1,0,0]
	s_nop 0
	v_pk_fma_f32 v[14:15], v[10:11], v[14:15], s[34:35] op_sel_hi:[1,1,0]
	s_nop 0
	v_pk_fma_f32 v[14:15], v[10:11], v[14:15], s[36:37] op_sel_hi:[1,1,0]
	s_nop 0
	v_pk_fma_f32 v[14:15], v[10:11], v[14:15], s[38:39] op_sel_hi:[1,1,0]
	s_nop 0
	v_pk_mul_f32 v[10:11], v[10:11], v[14:15]
	v_pk_mul_f32 v[14:15], v[6:7], v[6:7]
	s_nop 0
	v_pk_mul_f32 v[14:15], v[14:15], s[40:41] op_sel_hi:[1,0]
	s_nop 0
	v_exp_f32_e32 v14, v14
	v_exp_f32_e32 v15, v15
	s_nop 0
	v_pk_mul_f32 v[10:11], v[14:15], v[10:11]
	s_nop 0
	v_pk_mul_f32 v[14:15], v[6:7], v[10:11]
	v_pk_fma_f32 v[10:11], v[6:7], v[10:11], v[6:7] neg_lo:[1,0,0] neg_hi:[1,0,0]
	s_nop 0
	v_cndmask_b32_e32 v6, v10, v14, vcc
	v_cmp_gt_f32_e32 vcc, 0, v7
	v_mul_f32_e32 v6, v6, v8
	v_lshlrev_b32_e32 v8, 16, v9
	v_cndmask_b32_e32 v7, v11, v15, vcc
	v_mul_f32_e32 v4, v7, v4
	v_cvt_pk_bf16_f32 v4, v6, v4
	v_mov_b64_e32 v[10:11], v[50:51]
	v_mov_b64_e32 v[14:15], v[58:59]
	v_lshlrev_b32_e32 v6, 16, v13
	v_and_b32_e32 v7, 0xffff0000, v13
	v_and_b32_e32 v13, 0xffff0000, v17
	v_pk_mul_f32 v[6:7], v[20:21], v[6:7] op_sel_hi:[0,1]
	v_and_b32_e32 v9, 0xffff0000, v9
	v_pk_mul_f32 v[8:9], v[0:1], v[8:9] op_sel_hi:[0,1]
	s_waitcnt vmcnt(0)
	v_pk_mul_f32 v[12:13], v[14:15], v[12:13]
	s_nop 0
	v_pk_fma_f32 v[6:7], v[6:7], v[10:11], v[12:13]
	v_mov_b64_e32 v[10:11], v[66:67]
	s_waitcnt vmcnt(0)
	v_pk_fma_f32 v[6:7], v[8:9], v[10:11], v[6:7]
	v_mov_b64_e32 v[8:9], v[74:75]
	s_waitcnt vmcnt(0)
	v_pk_add_f32 v[6:7], v[8:9], v[6:7]
	s_nop 0
	v_and_b32_e32 v9, 0x7fffffff, v7
	v_and_b32_e32 v8, 0x7fffffff, v6
	v_pk_fma_f32 v[8:9], v[8:9], s[54:55], 1.0 op_sel_hi:[1,0,0]
	v_cmp_gt_f32_e32 vcc, 0, v6
	v_rcp_f32_e32 v8, v8
	v_rcp_f32_e32 v9, v9
	s_nop 0
	v_pk_fma_f32 v[10:11], v[8:9], s[12:13], v[30:31] op_sel_hi:[1,0,0]
	s_nop 0
	v_pk_fma_f32 v[10:11], v[8:9], v[10:11], s[34:35] op_sel_hi:[1,1,0]
	s_nop 0
	v_pk_fma_f32 v[10:11], v[8:9], v[10:11], s[36:37] op_sel_hi:[1,1,0]
	s_nop 0
	v_pk_fma_f32 v[10:11], v[8:9], v[10:11], s[38:39] op_sel_hi:[1,1,0]
	s_nop 0
	v_pk_mul_f32 v[8:9], v[8:9], v[10:11]
	v_pk_mul_f32 v[10:11], v[6:7], v[6:7]
	s_nop 0
	v_pk_mul_f32 v[10:11], v[10:11], s[40:41] op_sel_hi:[1,0]
	s_nop 0
	v_exp_f32_e32 v10, v10
	v_exp_f32_e32 v11, v11
	s_nop 0
	v_pk_mul_f32 v[8:9], v[10:11], v[8:9]
	s_nop 0
	v_pk_mul_f32 v[10:11], v[6:7], v[8:9]
	v_pk_fma_f32 v[8:9], v[6:7], v[8:9], v[6:7] neg_lo:[1,0,0] neg_hi:[1,0,0]
	s_nop 0
	v_cndmask_b32_e32 v0, v8, v10, vcc
	v_cmp_gt_f32_e32 vcc, 0, v7
	v_lshlrev_b32_e32 v7, 16, v5
	v_and_b32_e32 v5, 0xffff0000, v5
	v_cndmask_b32_e32 v6, v9, v11, vcc
	v_mul_f32_e32 v0, v0, v7
	v_mul_f32_e32 v5, v6, v5
	v_cvt_pk_bf16_f32 v5, v0, v5
	v_lshl_or_b32 v0, v34, 6, v35
	v_mov_b64_e32 v[6:7], s[20:21]
	s_nop 0
	v_mad_i64_i32 v[6:7], s[12:13], v0, s18, v[6:7]
	s_movk_i32 s12, 0x8ff
	v_add_u32_e32 v0, 0x200, v33
	v_cmp_lt_i32_e32 vcc, s12, v33
	v_lshl_add_u64 v[6:7], v[6:7], 0, v[18:19]
	s_or_b64 s[10:11], vcc, s[10:11]
	v_mov_b32_e32 v33, v0
	global_store_dwordx4 v[6:7], v[2:5], off
	s_andn2_b64 exec, exec, s[10:11]
	s_cbranch_execz .LBB0_804

;     __device__ bool next(int i, Unit& u) const {
;         const long L = (long)lo + (long)i * G + c; if (L >= hi) return false; u.L = (int)L;
;         int wgid = (int)L; { const int q = nwg / NXCD, r = nwg % NXCD, xcd = wgid % NXCD, off = wgid / NXCD; wgid = (xcd < r ? xcd * (q + 1) : r * (q + 1) + (xcd - r) * q) + off; }
;         const int nig = WGM * nN, gid = wgid / nig, fm = gid * WGM, gsz = (nM - fm) < WGM ? (nM - fm) : WGM;
;         u.pm = fm + ((wgid % nig) % gsz); u.pn = (wgid % nig) / gsz; return true;
.LBB0_837:
	s_add_i32 s72, s72, 1
	v_readlane_b32 s14, v255, 18
	s_mul_i32 s12, s72, s0
	s_mul_hi_u32 s13, s72, s14
	s_add_i32 s13, s13, s12
	s_mul_i32 s12, s72, s14
	s_add_u32 s12, s12, s77
	s_addc_u32 s13, s13, s24
	s_waitcnt lgkmcnt(0)
	v_mov_b64_e32 v[2:3], 0x100
	s_nop 0
	v_cmp_lt_i64_e64 s[42:43], s[12:13], v[2:3]
	v_mov_b64_e32 v[2:3], 0xff
	s_nop 0
	v_cmp_gt_i64_e64 s[40:41], s[12:13], v[2:3]
	s_and_b64 vcc, exec, s[40:41]
	s_cbranch_vccnz .LBB0_843
	s_ashr_i32 s13, s12, 31
	s_lshr_b32 s13, s13, 29
	s_add_i32 s14, s12, s13
	s_and_b32 s13, s14, -8
	s_sub_i32 s15, s12, s13
	s_cmp_gt_i32 s15, -1
	s_mov_b64 s[12:13], -1
	s_cbranch_scc0 .LBB0_840
	s_lshl_b32 s34, s15, 5
	s_mov_b64 s[12:13], 0

;     __device__ bool next(int i, Unit& u) const {
;         const long L = (long)lo + (long)i * G + c; if (L >= hi) return false; u.L = (int)L;
;         int wgid = (int)L; { const int q = nwg / NXCD, r = nwg % NXCD, xcd = wgid % NXCD, off = wgid / NXCD; wgid = (xcd < r ? xcd * (q + 1) : r * (q + 1) + (xcd - r) * q) + off; }
;         const int nig = WGM * nN, gid = wgid / nig, fm = gid * WGM, gsz = (nM - fm) < WGM ? (nM - fm) : WGM;
;         u.pm = fm + ((wgid % nig) % gsz); u.pn = (wgid % nig) / gsz; return true;
.LBB0_880:
	s_add_i32 s86, s86, 1
	v_readlane_b32 s0, v255, 18
	s_mul_i32 s18, s86, s84
	s_mul_hi_u32 s19, s86, s0
	s_add_i32 s19, s19, s18
	s_mul_i32 s18, s86, s0
	v_readlane_b32 s0, v255, 19
	s_add_u32 s18, s18, s0
	s_addc_u32 s19, s19, s82
	v_mov_b64_e32 v[2:3], 0x580
	s_nop 0
	v_cmp_lt_i64_e64 s[42:43], s[18:19], v[2:3]
	v_mov_b64_e32 v[2:3], 0x57f
	s_nop 0
	v_cmp_gt_i64_e64 s[40:41], s[18:19], v[2:3]
	s_and_b64 vcc, exec, s[40:41]
	s_cbranch_vccnz .LBB0_882
	s_ashr_i32 s19, s18, 31
	s_lshr_b32 s19, s19, 29
	s_add_i32 s19, s18, s19
	s_ashr_i32 s34, s19, 3
	s_and_b32 s19, s19, -8
	s_sub_i32 s18, s18, s19
	s_cmp_lt_i32 s18, 0
	s_movk_i32 s0, 0xb1
	s_cselect_b32 s19, s0, 0xb0
	s_mul_i32 s18, s18, s19
	s_add_i32 s18, s18, s34
	s_mul_hi_i32 s19, s18, 0x2e8ba2e9
	s_lshr_b32 s34, s19, 31
	s_ashr_i32 s19, s19, 5
	s_add_i32 s19, s19, s34
	s_lshl_b32 s34, s19, 3
	s_sub_i32 s35, 64, s34
	s_min_i32 s35, s35, 8
	s_abs_i32 s44, s35
	v_cvt_f32_u32_e32 v2, s44
	s_sub_i32 s50, 0, s44
	s_mulk_i32 s19, 0xb0
	s_sub_i32 s18, s18, s19
	v_rcp_iflag_f32_e32 v2, v2
	s_abs_i32 s19, s18
	s_xor_b32 s45, s18, s35
	s_ashr_i32 s45, s45, 31
	v_mul_f32_e32 v2, 0x4f7ffffe, v2
	v_cvt_u32_f32_e32 v2, v2
	s_nop 0
	v_readfirstlane_b32 s51, v2
	s_mul_i32 s50, s50, s51
	s_mul_hi_u32 s50, s51, s50
	s_add_i32 s51, s51, s50
	s_mul_hi_u32 s50, s19, s51
	s_mul_i32 s51, s50, s44
	s_sub_i32 s19, s19, s51
	s_add_i32 s52, s50, 1
	s_sub_i32 s51, s19, s44
	s_cmp_ge_u32 s19, s44
	s_cselect_b32 s50, s52, s50
	s_cselect_b32 s19, s51, s19
	s_add_i32 s51, s50, 1
	s_cmp_ge_u32 s19, s44
	s_cselect_b32 s19, s51, s50
	s_xor_b32 s19, s19, s45
	s_sub_i32 s87, s19, s45
	s_mul_i32 s19, s87, s35
	s_sub_i32 s18, s18, s19
	s_add_i32 s88, s34, s18

;     __device__ bool next(int i, Unit& u) const {
;         const long L = (long)lo + (long)i * G + c; if (L >= hi) return false; u.L = (int)L;
;         int wgid = (int)L; { const int q = nwg / NXCD, r = nwg % NXCD, xcd = wgid % NXCD, off = wgid / NXCD; wgid = (xcd < r ? xcd * (q + 1) : r * (q + 1) + (xcd - r) * q) + off; }
;         const int nig = WGM * nN, gid = wgid / nig, fm = gid * WGM, gsz = (nM - fm) < WGM ? (nM - fm) : WGM;
;         u.pm = fm + ((wgid % nig) % gsz); u.pn = (wgid % nig) / gsz; return true;
.LBB0_962:
	s_add_i32 s53, s53, 1
	s_mul_i32 s8, s53, s72
	s_mul_hi_u32 s9, s53, s48
	s_add_i32 s9, s9, s8
	s_mul_i32 s8, s53, s48
	s_add_u32 s8, s8, s0
	s_addc_u32 s9, s9, 0
	v_mov_b64_e32 v[2:3], 0x100
	s_nop 0
	v_cmp_lt_i64_e64 s[42:43], s[8:9], v[2:3]
	v_mov_b64_e32 v[2:3], 0xff
	s_nop 0
	v_cmp_gt_i64_e64 s[40:41], s[8:9], v[2:3]
	s_and_b64 vcc, exec, s[40:41]
	s_cbranch_vccnz .LBB0_968
	s_ashr_i32 s9, s8, 31
	s_lshr_b32 s9, s9, 29
	s_add_i32 s9, s8, s9
	s_and_b32 s10, s9, -8
	s_sub_i32 s16, s8, s10
	s_cmp_gt_i32 s16, -1
	s_mov_b64 s[10:11], -1
	s_cbranch_scc0 .LBB0_965
	s_lshl_b32 s17, s16, 6
	s_mov_b64 s[10:11], 0
